# attention tile loop hand-rewritten: single body, K-frag prefetch ring, DMA issue spread in QK, counted lgkmcnt in PV, no permlane (V key permutation)
# speedup vs baseline: 1.0521x; 1.0413x over previous
.LBB0_265:
	s_or_b64 exec, exec, s[6:7]
	v_ashrrev_i32_e32 v0, 4, v211
	v_lshlrev_b32_e32 v2, 13, v0
	v_bitop3_b32 v3, v211, v0, 15 bitop3:0x6c
	v_ashrrev_i32_e32 v218, 5, v211
	v_lshl_add_u32 v2, v3, 4, v2
	v_lshlrev_b32_e32 v0, 3, v0
	v_bfe_u32 v3, v211, 2, 2
	s_and_b32 s5, s72, 1
	s_sub_i32 s6, 0x7f, s3
	v_and_or_b32 v0, v0, 8, v3
	v_lshlrev_b32_e32 v3, 6, v218
	s_cmp_eq_u32 s5, 0
	v_lshl_add_u32 v0, v0, 13, v3
	v_lshlrev_b32_e32 v6, 4, v211
	s_cselect_b32 s5, s6, s3
	v_and_or_b32 v0, v6, 48, v0
	s_lshl_b32 s90, s4, 9
	v_cndmask_b32_e64 v7, v0, v2, s[0:1]
	s_add_i32 s7, s90, s93
	v_add_u32_e32 v0, s7, v7
	s_mov_b32 s8, m0
	s_mov_b32 m0, s97
	s_nop 0
	global_load_lds_dwordx4 v0, s[62:63]
	s_mov_b32 m0, s8
	s_lshl_b32 s6, s5, 7
	v_readlane_b32 s8, v254, 21
	v_readlane_b32 s3, v254, 28
	v_and_b32_e32 v217, 31, v211
	v_xor_b32_e32 v8, s8, v7
	v_add_u32_e32 v2, s7, v8
	v_readlane_b32 s8, v254, 40
	s_or_b32 s3, s6, s3
	s_lshl_b32 s82, s4, 8
	v_add_u32_e32 v3, s8, v2
	s_mov_b32 s8, m0
	s_mov_b32 m0, s75
	s_nop 0
	global_load_lds_dwordx4 v3, s[62:63]
	s_mov_b32 m0, s8
	s_ashr_i32 s83, s82, 31
	v_readlane_b32 s8, v254, 20
	v_readlane_b32 s4, v254, 24
	v_mov_b32_e32 v14, v1
	v_xor_b32_e32 v9, s8, v7
	v_add_u32_e32 v3, s7, v9
	v_readlane_b32 s8, v254, 36
	v_mov_b32_e32 v15, v1
	v_add_u32_e32 v231, s93, v7
	v_add_u32_e32 v4, s8, v3
	s_mov_b32 s8, m0
	s_mov_b32 m0, s68
	s_nop 0
	global_load_lds_dwordx4 v4, s[62:63]
	s_mov_b32 m0, s8
	v_mov_b32_e32 v11, v1
	v_readlane_b32 s8, v254, 19
	v_mov_b32_e32 v12, v1
	v_mov_b32_e32 v13, v1
	v_xor_b32_e32 v10, s8, v7
	v_add_u32_e32 v4, s7, v10
	v_readlane_b32 s7, v254, 32
	v_readlane_b32 s8, v254, 44
	v_readlane_b32 s9, v254, 45
	v_add_u32_e32 v5, s7, v4
	s_mov_b32 s7, m0
	s_mov_b32 m0, s69
	s_nop 0
	global_load_lds_dwordx4 v5, s[62:63]
	s_mov_b32 m0, s7
	s_mov_b32 s91, 0
	v_readlane_b32 s7, v254, 42
	s_lshl_b32 s88, s5, 1
	s_lshr_b32 s89, s3, 6
	v_add_u32_e32 v0, s7, v0
	s_mov_b32 s7, m0
	s_mov_b32 m0, s78
	s_nop 0
	global_load_lds_dwordx4 v0, s[62:63]
	s_mov_b32 m0, s7
	s_add_i32 s73, s3, 0xffffff10
	v_readlane_b32 s7, v254, 38
	v_cmp_gt_u32_e64 s[36:37], 32, v211
	v_lshl_add_u32 v220, v217, 2, s96
	v_add_u32_e32 v0, s7, v2
	s_mov_b32 s7, m0
	s_mov_b32 m0, s79
	s_nop 0
	global_load_lds_dwordx4 v0, s[62:63]
	s_mov_b32 m0, s7
	v_lshlrev_b32_e32 v219, 4, v218
	v_readlane_b32 s7, v254, 34
	v_mov_b32_e32 v233, 0xf149f2ca
	v_mov_b32_e32 v232, 0
	v_add_u32_e32 v0, s7, v3
	s_mov_b32 s7, m0
	s_mov_b32 m0, s54
	s_nop 0
	global_load_lds_dwordx4 v0, s[62:63]
	s_mov_b32 m0, s7
	s_mov_b32 s58, 0
	v_readlane_b32 s7, v254, 30
	s_nop 1
	v_add_u32_e32 v0, s7, v4
	s_mov_b32 s7, m0
	s_mov_b32 m0, s55
	s_nop 0
	global_load_lds_dwordx4 v0, s[62:63]
	s_mov_b32 m0, s7
	v_or_b32_e32 v0, s3, v217
	v_lshlrev_b32_e32 v0, 13, v0
	v_lshl_add_u64 v[2:3], s[42:43], 0, v[0:1]
	v_lshl_add_u64 v[2:3], s[82:83], 1, v[2:3]
	v_lshlrev_b32_e32 v4, 3, v218
	v_lshl_add_u64 v[2:3], v[2:3], 0, s[8:9]
	v_ashrrev_i32_e32 v5, 31, v4
	v_lshl_add_u64 v[2:3], v[4:5], 1, v[2:3]
	global_load_dwordx4 v[178:181], v[2:3], off
	global_load_dwordx4 v[182:185], v[2:3], off offset:32
	global_load_dwordx4 v[186:189], v[2:3], off offset:64
	global_load_dwordx4 v[190:193], v[2:3], off offset:96
	global_load_dwordx4 v[194:197], v[2:3], off offset:128
	global_load_dwordx4 v[198:201], v[2:3], off offset:160
	global_load_dwordx4 v[202:205], v[2:3], off offset:192
	global_load_dwordx4 v[206:209], v[2:3], off offset:224
	v_lshlrev_b32_e32 v2, 3, v211
	v_and_b32_e32 v3, 0xc0, v6
	v_lshlrev_b32_e32 v4, 1, v211
	v_and_or_b32 v3, v2, 24, v3
	v_and_b32_e32 v4, 32, v4
	v_lshlrev_b32_e32 v2, 7, v211
	v_and_b32_e32 v2, 0x1000, v2
	v_or3_b32 v2, v3, v4, v2
	v_lshl_or_b32 v3, v217, 8, s4
	s_add_i32 s4, 0, 0x8000
	v_add_u32_e32 v222, s4, v2
	v_readlane_b32 s4, v254, 29
	s_add_i32 s4, s4, s6
	v_bitop3_b32 v0, v211, v218, 15 bitop3:0x6c
	v_add_u32_e32 v2, s4, v217
	v_readlane_b32 s4, v254, 31
	v_lshl_add_u32 v221, v0, 4, v3
	v_lshlrev_b32_e32 v0, 2, v218
	v_add_u32_e32 v224, s4, v10
	v_readlane_b32 s4, v254, 33
	v_sub_u32_e32 v223, v2, v0
	v_mov_b32_e32 v0, v1
	v_add_u32_e32 v225, s4, v10
	v_readlane_b32 s4, v254, 35
	v_mov_b32_e32 v2, v1
	v_mov_b32_e32 v3, v1
	v_add_u32_e32 v226, s4, v9
	v_readlane_b32 s4, v254, 37
	v_mov_b32_e32 v4, v1
	v_mov_b32_e32 v5, v1
	v_add_u32_e32 v227, s4, v9
	v_readlane_b32 s4, v254, 39
	v_mov_b32_e32 v6, v1
	v_mov_b32_e32 v9, v1
	v_add_u32_e32 v228, s4, v8
	v_readlane_b32 s4, v254, 41
	v_mov_b32_e32 v10, v1
	s_nop 0
	v_add_u32_e32 v229, s4, v8
	v_readlane_b32 s4, v254, 43
	v_mov_b32_e32 v8, v1
	s_nop 0
	v_add_u32_e32 v230, s4, v7
	v_mov_b32_e32 v7, v1
	v_mov_b64_e32 v[128:129], v[14:15]
	v_mov_b64_e32 v[112:113], v[14:15]
	v_mov_b64_e32 v[96:97], v[14:15]
	v_mov_b64_e32 v[80:81], v[14:15]
	v_mov_b64_e32 v[64:65], v[14:15]
	v_mov_b64_e32 v[48:49], v[14:15]
	v_mov_b64_e32 v[32:33], v[14:15]
	v_mov_b64_e32 v[126:127], v[12:13]
	v_mov_b64_e32 v[124:125], v[10:11]
	v_mov_b64_e32 v[122:123], v[8:9]
	v_mov_b64_e32 v[120:121], v[6:7]
	v_mov_b64_e32 v[118:119], v[4:5]
	v_mov_b64_e32 v[116:117], v[2:3]
	v_mov_b64_e32 v[114:115], v[0:1]
	v_mov_b64_e32 v[110:111], v[12:13]
	v_mov_b64_e32 v[108:109], v[10:11]
	v_mov_b64_e32 v[106:107], v[8:9]
	v_mov_b64_e32 v[104:105], v[6:7]
	v_mov_b64_e32 v[102:103], v[4:5]
	v_mov_b64_e32 v[100:101], v[2:3]
	v_mov_b64_e32 v[98:99], v[0:1]
	v_mov_b64_e32 v[94:95], v[12:13]
	v_mov_b64_e32 v[92:93], v[10:11]
	v_mov_b64_e32 v[90:91], v[8:9]
	v_mov_b64_e32 v[88:89], v[6:7]
	v_mov_b64_e32 v[86:87], v[4:5]
	v_mov_b64_e32 v[84:85], v[2:3]
	v_mov_b64_e32 v[82:83], v[0:1]
	v_mov_b64_e32 v[78:79], v[12:13]
	v_mov_b64_e32 v[76:77], v[10:11]
	v_mov_b64_e32 v[74:75], v[8:9]
	v_mov_b64_e32 v[72:73], v[6:7]
	v_mov_b64_e32 v[70:71], v[4:5]
	v_mov_b64_e32 v[68:69], v[2:3]
	v_mov_b64_e32 v[66:67], v[0:1]
	v_mov_b64_e32 v[62:63], v[12:13]
	v_mov_b64_e32 v[60:61], v[10:11]
	v_mov_b64_e32 v[58:59], v[8:9]
	v_mov_b64_e32 v[56:57], v[6:7]
	v_mov_b64_e32 v[54:55], v[4:5]
	v_mov_b64_e32 v[52:53], v[2:3]
	v_mov_b64_e32 v[50:51], v[0:1]
	v_mov_b64_e32 v[46:47], v[12:13]
	v_mov_b64_e32 v[44:45], v[10:11]
	v_mov_b64_e32 v[42:43], v[8:9]
	v_mov_b64_e32 v[40:41], v[6:7]
	v_mov_b64_e32 v[38:39], v[4:5]
	v_mov_b64_e32 v[36:37], v[2:3]
	v_mov_b64_e32 v[34:35], v[0:1]
	v_mov_b64_e32 v[30:31], v[12:13]
	v_mov_b64_e32 v[28:29], v[10:11]
	v_mov_b64_e32 v[26:27], v[8:9]
	v_mov_b64_e32 v[24:25], v[6:7]
	v_mov_b64_e32 v[22:23], v[4:5]
	v_mov_b64_e32 v[20:21], v[2:3]
	v_mov_b64_e32 v[18:19], v[0:1]
	v_mov_b64_e32 v[16:17], v[14:15]
	v_mov_b64_e32 v[14:15], v[12:13]
	v_mov_b64_e32 v[12:13], v[10:11]
	v_mov_b64_e32 v[10:11], v[8:9]
	v_mov_b64_e32 v[8:9], v[6:7]
	v_mov_b64_e32 v[6:7], v[4:5]
	v_mov_b64_e32 v[4:5], v[2:3]
	v_mov_b64_e32 v[2:3], v[0:1]
	s_branch .Lat_entry
.Lat_entry:
	s_mov_b32 s92, m0
	s_add_i32 s71, s97, 0x10000
	s_mov_b32 s70, 0
	s_movk_i32 s81, 0x7f
	s_mov_b32 s50, 0x20000
	s_add_i32 s51, s90, 0x80000
	v_add_u32_e32 v231, s51, v231
	v_add_u32_e32 v229, s51, v229
	v_add_u32_e32 v227, s51, v227
	v_add_u32_e32 v225, s51, v225
	v_add_u32_e32 v230, s51, v230
	v_add_u32_e32 v228, s51, v228
	v_add_u32_e32 v226, s51, v226
	v_add_u32_e32 v224, s51, v224
	v_add_u32_e32 v223, 0x5b, v223
.Lat_loop:
	s_waitcnt vmcnt(0) lgkmcnt(0)
	s_barrier
	s_cmp_gt_u32 s58, s89
	s_cbranch_scc1 .Lat_inactive
	v_xor_b32_e32 v234, s70, v221
	ds_read_b128 v[162:165], v234
	v_xor_b32_e32 v235, 32, v234
	ds_read_b128 v[166:169], v235
	v_xor_b32_e32 v236, 64, v234
	ds_read_b128 v[170:173], v236
	v_xor_b32_e32 v237, 0x60, v234
	ds_read_b128 v[174:177], v237
	v_xor_b32_e32 v238, 0x80, v234
	v_xor_b32_e32 v239, 0xa0, v234
	v_xor_b32_e32 v240, 0xc0, v234
	v_xor_b32_e32 v241, 0xe0, v234
	v_add_u32_e32 v242, s70, v222
	s_add_i32 m0, s71, 0x0
	s_nop 0
	global_load_lds_dwordx4 v231, s[62:63]
	v_add_u32_e32 v231, 0x80000, v231
	s_add_i32 m0, s71, 0x400
	s_nop 0
	global_load_lds_dwordx4 v229, s[62:63]
	v_add_u32_e32 v229, 0x80000, v229
	s_waitcnt lgkmcnt(3)
	v_mfma_f32_32x32x16_bf16 v[146:161], v[162:165], v[178:181], 0
	ds_read_b128 v[162:165], v238
	s_waitcnt lgkmcnt(3)
	v_mfma_f32_32x32x16_bf16 v[146:161], v[166:169], v[182:185], v[146:161]
	ds_read_b128 v[166:169], v239
	s_add_i32 m0, s71, 0x800
	s_nop 0
	global_load_lds_dwordx4 v227, s[62:63]
	v_add_u32_e32 v227, 0x80000, v227
	s_waitcnt lgkmcnt(3)
	v_mfma_f32_32x32x16_bf16 v[146:161], v[170:173], v[186:189], v[146:161]
	ds_read_b128 v[170:173], v240
	s_waitcnt lgkmcnt(3)
	v_mfma_f32_32x32x16_bf16 v[146:161], v[174:177], v[190:193], v[146:161]
	ds_read_b128 v[174:177], v241
	s_add_i32 m0, s71, 0xc00
	s_nop 0
	global_load_lds_dwordx4 v225, s[62:63]
	v_add_u32_e32 v225, 0x80000, v225
	s_waitcnt lgkmcnt(3)
	v_mfma_f32_32x32x16_bf16 v[146:161], v[162:165], v[194:197], v[146:161]
	ds_read_b128 v[162:165], v234 offset:8192
	s_waitcnt lgkmcnt(3)
	v_mfma_f32_32x32x16_bf16 v[146:161], v[166:169], v[198:201], v[146:161]
	ds_read_b128 v[166:169], v235 offset:8192
	s_add_i32 m0, s71, 0x1000
	s_nop 0
	global_load_lds_dwordx4 v230, s[62:63]
	v_add_u32_e32 v230, 0x80000, v230
	s_waitcnt lgkmcnt(3)
	v_mfma_f32_32x32x16_bf16 v[146:161], v[170:173], v[202:205], v[146:161]
	ds_read_b128 v[170:173], v236 offset:8192
	s_waitcnt lgkmcnt(3)
	v_mfma_f32_32x32x16_bf16 v[146:161], v[174:177], v[206:209], v[146:161]
	ds_read_b128 v[174:177], v237 offset:8192
	s_add_i32 m0, s71, 0x1400
	s_nop 0
	global_load_lds_dwordx4 v228, s[62:63]
	v_add_u32_e32 v228, 0x80000, v228
	s_waitcnt lgkmcnt(3)
	v_mfma_f32_32x32x16_bf16 v[130:145], v[162:165], v[178:181], 0
	ds_read_b128 v[162:165], v238 offset:8192
	s_waitcnt lgkmcnt(3)
	v_mfma_f32_32x32x16_bf16 v[130:145], v[166:169], v[182:185], v[130:145]
	ds_read_b128 v[166:169], v239 offset:8192
	s_add_i32 m0, s71, 0x1800
	s_nop 0
	global_load_lds_dwordx4 v226, s[62:63]
	v_add_u32_e32 v226, 0x80000, v226
	s_waitcnt lgkmcnt(3)
	v_mfma_f32_32x32x16_bf16 v[130:145], v[170:173], v[186:189], v[130:145]
	ds_read_b128 v[170:173], v240 offset:8192
	s_waitcnt lgkmcnt(3)
	v_mfma_f32_32x32x16_bf16 v[130:145], v[174:177], v[190:193], v[130:145]
	ds_read_b128 v[174:177], v241 offset:8192
	s_add_i32 m0, s71, 0x1c00
	s_nop 0
	global_load_lds_dwordx4 v224, s[62:63]
	v_add_u32_e32 v224, 0x80000, v224
	s_waitcnt lgkmcnt(3)
	v_mfma_f32_32x32x16_bf16 v[130:145], v[162:165], v[194:197], v[130:145]
	ds_read_b64_tr_b16 v[162:163], v242 offset:0
	ds_read_b64_tr_b16 v[164:165], v242 offset:256
	s_waitcnt lgkmcnt(4)
	v_mfma_f32_32x32x16_bf16 v[130:145], v[166:169], v[198:201], v[130:145]
	ds_read_b64_tr_b16 v[166:167], v242 offset:8192
	ds_read_b64_tr_b16 v[168:169], v242 offset:8448
	s_waitcnt lgkmcnt(5)
	v_mfma_f32_32x32x16_bf16 v[130:145], v[170:173], v[202:205], v[130:145]
	ds_read_b64_tr_b16 v[170:171], v242 offset:16384
	ds_read_b64_tr_b16 v[172:173], v242 offset:16640
	s_waitcnt lgkmcnt(6)
	v_mfma_f32_32x32x16_bf16 v[130:145], v[174:177], v[206:209], v[130:145]
	ds_read_b64_tr_b16 v[174:175], v242 offset:24576
	ds_read_b64_tr_b16 v[176:177], v242 offset:24832
	s_add_i32 s4, s91, 0xb0
	s_cmp_le_u32 s4, s3
	s_cbranch_scc0 .Lat_diag_a
.Lat_sm_a:
	v_max3_f32 v0, v146, v147, v148
	v_max3_f32 v0, v0, v149, v150
	v_max3_f32 v0, v0, v151, v152
	v_max3_f32 v0, v0, v153, v154
	v_max3_f32 v0, v0, v155, v156
	v_max3_f32 v234, v157, v158, v159
	v_max3_f32 v234, v234, v160, v161
	s_nop 1
	v_max3_f32 v235, v136, v137, v138
	v_max3_f32 v234, v234, v130, v131
	v_max3_f32 v235, v235, v139, v140
	v_max3_f32 v234, v234, v132, v133
	v_max3_f32 v235, v235, v141, v142
	v_max3_f32 v234, v234, v134, v135
	v_max3_f32 v235, v235, v143, v144
	v_max_f32_e32 v235, v235, v145
	v_max3_f32 v234, v0, v234, v235
	v_mov_b32_e32 v235, v234
	s_nop 1
	v_permlane32_swap_b32_e32 v234, v235
	v_max_f32_e32 v234, v234, v235
	v_sub_f32_e32 v235, v234, v233
	v_cmp_ge_f32_e32 vcc, s74, v235
	s_cmp_eq_u64 vcc, exec
	s_cbranch_scc0 .Lat_resc_a
.Lat_exp_a:
	v_sub_f32_e32 v146, v146, v233
	v_exp_f32_e32 v146, v146
	v_sub_f32_e32 v147, v147, v233
	v_exp_f32_e32 v147, v147
	v_sub_f32_e32 v148, v148, v233
	v_add_f32_e32 v0, v146, v147
	v_exp_f32_e32 v148, v148
	v_sub_f32_e32 v149, v149, v233
	v_add_f32_e32 v0, v0, v148
	v_exp_f32_e32 v149, v149
	v_sub_f32_e32 v150, v150, v233
	v_add_f32_e32 v0, v0, v149
	v_exp_f32_e32 v150, v150
	v_sub_f32_e32 v151, v151, v233
	v_add_f32_e32 v0, v0, v150
	v_exp_f32_e32 v151, v151
	v_sub_f32_e32 v152, v152, v233
	v_add_f32_e32 v0, v0, v151
	v_exp_f32_e32 v152, v152
	v_sub_f32_e32 v153, v153, v233
	v_add_f32_e32 v0, v0, v152
	v_exp_f32_e32 v153, v153
	v_sub_f32_e32 v154, v154, v233
	v_add_f32_e32 v0, v0, v153
	v_exp_f32_e32 v154, v154
	v_sub_f32_e32 v155, v155, v233
	v_add_f32_e32 v0, v0, v154
	v_exp_f32_e32 v155, v155
	v_sub_f32_e32 v156, v156, v233
	v_add_f32_e32 v0, v0, v155
	v_exp_f32_e32 v156, v156
	v_sub_f32_e32 v157, v157, v233
	v_add_f32_e32 v0, v0, v156
	v_exp_f32_e32 v157, v157
	v_sub_f32_e32 v158, v158, v233
	v_add_f32_e32 v0, v0, v157
	v_exp_f32_e32 v158, v158
	v_sub_f32_e32 v159, v159, v233
	v_add_f32_e32 v0, v0, v158
	v_exp_f32_e32 v159, v159
	v_sub_f32_e32 v160, v160, v233
	v_add_f32_e32 v0, v0, v159
	v_exp_f32_e32 v160, v160
	v_sub_f32_e32 v161, v161, v233
	v_add_f32_e32 v0, v0, v160
	v_exp_f32_e32 v161, v161
	v_sub_f32_e32 v130, v130, v233
	v_add_f32_e32 v0, v0, v161
	v_exp_f32_e32 v130, v130
	v_sub_f32_e32 v131, v131, v233
	v_add_f32_e32 v0, v0, v130
	v_exp_f32_e32 v131, v131
	v_sub_f32_e32 v132, v132, v233
	v_add_f32_e32 v0, v0, v131
	v_exp_f32_e32 v132, v132
	v_sub_f32_e32 v133, v133, v233
	v_add_f32_e32 v0, v0, v132
	v_exp_f32_e32 v133, v133
	v_sub_f32_e32 v134, v134, v233
	v_add_f32_e32 v0, v0, v133
	v_exp_f32_e32 v134, v134
	v_sub_f32_e32 v135, v135, v233
	v_add_f32_e32 v0, v0, v134
	v_exp_f32_e32 v135, v135
	v_sub_f32_e32 v136, v136, v233
	v_add_f32_e32 v0, v0, v135
	v_exp_f32_e32 v136, v136
	v_sub_f32_e32 v137, v137, v233
	v_add_f32_e32 v0, v0, v136
	v_exp_f32_e32 v137, v137
	v_sub_f32_e32 v138, v138, v233
	v_add_f32_e32 v0, v0, v137
	v_exp_f32_e32 v138, v138
	v_sub_f32_e32 v139, v139, v233
	v_add_f32_e32 v0, v0, v138
	v_exp_f32_e32 v139, v139
	v_sub_f32_e32 v140, v140, v233
	v_add_f32_e32 v0, v0, v139
	v_exp_f32_e32 v140, v140
	v_sub_f32_e32 v141, v141, v233
	v_add_f32_e32 v0, v0, v140
	v_exp_f32_e32 v141, v141
	v_sub_f32_e32 v142, v142, v233
	v_add_f32_e32 v0, v0, v141
	v_exp_f32_e32 v142, v142
	v_sub_f32_e32 v143, v143, v233
	v_add_f32_e32 v0, v0, v142
	v_exp_f32_e32 v143, v143
	v_sub_f32_e32 v144, v144, v233
	v_add_f32_e32 v0, v0, v143
	v_exp_f32_e32 v144, v144
	v_sub_f32_e32 v145, v145, v233
	v_add_f32_e32 v0, v0, v144
	v_exp_f32_e32 v145, v145
	v_cvt_pk_bf16_f32 v146, v146, v147
	v_cvt_pk_bf16_f32 v147, v148, v149
	v_cvt_pk_bf16_f32 v148, v150, v151
	v_cvt_pk_bf16_f32 v149, v152, v153
	v_cvt_pk_bf16_f32 v150, v154, v155
	v_cvt_pk_bf16_f32 v151, v156, v157
	v_cvt_pk_bf16_f32 v152, v158, v159
	v_cvt_pk_bf16_f32 v153, v160, v161
	v_add_f32_e32 v0, v0, v145
	v_add_f32_e32 v232, v232, v0
	v_cvt_pk_bf16_f32 v130, v130, v131
	v_cvt_pk_bf16_f32 v131, v132, v133
	v_cvt_pk_bf16_f32 v132, v134, v135
	v_cvt_pk_bf16_f32 v133, v136, v137
	v_cvt_pk_bf16_f32 v134, v138, v139
	v_cvt_pk_bf16_f32 v135, v140, v141
	v_cvt_pk_bf16_f32 v136, v142, v143
	v_cvt_pk_bf16_f32 v137, v144, v145
	s_waitcnt lgkmcnt(6)
	v_mfma_f32_32x32x16_bf16 v[114:129], v[146:149], v[162:165], v[114:129]
	ds_read_b64_tr_b16 v[162:163], v242 offset:512
	ds_read_b64_tr_b16 v[164:165], v242 offset:768
	s_waitcnt lgkmcnt(6)
	v_mfma_f32_32x32x16_bf16 v[114:129], v[150:153], v[166:169], v[114:129]
	ds_read_b64_tr_b16 v[166:167], v242 offset:8704
	ds_read_b64_tr_b16 v[168:169], v242 offset:8960
	s_waitcnt lgkmcnt(6)
	v_mfma_f32_32x32x16_bf16 v[114:129], v[130:133], v[170:173], v[114:129]
	ds_read_b64_tr_b16 v[170:171], v242 offset:16896
	ds_read_b64_tr_b16 v[172:173], v242 offset:17152
	s_waitcnt lgkmcnt(6)
	v_mfma_f32_32x32x16_bf16 v[114:129], v[134:137], v[174:177], v[114:129]
	ds_read_b64_tr_b16 v[174:175], v242 offset:25088
	ds_read_b64_tr_b16 v[176:177], v242 offset:25344
	s_waitcnt lgkmcnt(6)
	v_mfma_f32_32x32x16_bf16 v[98:113], v[146:149], v[162:165], v[98:113]
	ds_read_b64_tr_b16 v[162:163], v242 offset:1024
	ds_read_b64_tr_b16 v[164:165], v242 offset:1280
	s_waitcnt lgkmcnt(6)
	v_mfma_f32_32x32x16_bf16 v[98:113], v[150:153], v[166:169], v[98:113]
	ds_read_b64_tr_b16 v[166:167], v242 offset:9216
	ds_read_b64_tr_b16 v[168:169], v242 offset:9472
	s_waitcnt lgkmcnt(6)
	v_mfma_f32_32x32x16_bf16 v[98:113], v[130:133], v[170:173], v[98:113]
	ds_read_b64_tr_b16 v[170:171], v242 offset:17408
	ds_read_b64_tr_b16 v[172:173], v242 offset:17664
	s_waitcnt lgkmcnt(6)
	v_mfma_f32_32x32x16_bf16 v[98:113], v[134:137], v[174:177], v[98:113]
	ds_read_b64_tr_b16 v[174:175], v242 offset:25600
	ds_read_b64_tr_b16 v[176:177], v242 offset:25856
	s_waitcnt lgkmcnt(6)
	v_mfma_f32_32x32x16_bf16 v[82:97], v[146:149], v[162:165], v[82:97]
	ds_read_b64_tr_b16 v[162:163], v242 offset:1536
	ds_read_b64_tr_b16 v[164:165], v242 offset:1792
	s_waitcnt lgkmcnt(6)
	v_mfma_f32_32x32x16_bf16 v[82:97], v[150:153], v[166:169], v[82:97]
	ds_read_b64_tr_b16 v[166:167], v242 offset:9728
	ds_read_b64_tr_b16 v[168:169], v242 offset:9984
	s_waitcnt lgkmcnt(6)
	v_mfma_f32_32x32x16_bf16 v[82:97], v[130:133], v[170:173], v[82:97]
	ds_read_b64_tr_b16 v[170:171], v242 offset:17920
	ds_read_b64_tr_b16 v[172:173], v242 offset:18176
	s_waitcnt lgkmcnt(6)
	v_mfma_f32_32x32x16_bf16 v[82:97], v[134:137], v[174:177], v[82:97]
	ds_read_b64_tr_b16 v[174:175], v242 offset:26112
	ds_read_b64_tr_b16 v[176:177], v242 offset:26368
	s_waitcnt lgkmcnt(6)
	v_mfma_f32_32x32x16_bf16 v[66:81], v[146:149], v[162:165], v[66:81]
	ds_read_b64_tr_b16 v[162:163], v242 offset:2048
	ds_read_b64_tr_b16 v[164:165], v242 offset:2304
	s_waitcnt lgkmcnt(6)
	v_mfma_f32_32x32x16_bf16 v[66:81], v[150:153], v[166:169], v[66:81]
	ds_read_b64_tr_b16 v[166:167], v242 offset:10240
	ds_read_b64_tr_b16 v[168:169], v242 offset:10496
	s_waitcnt lgkmcnt(6)
	v_mfma_f32_32x32x16_bf16 v[66:81], v[130:133], v[170:173], v[66:81]
	ds_read_b64_tr_b16 v[170:171], v242 offset:18432
	ds_read_b64_tr_b16 v[172:173], v242 offset:18688
	s_waitcnt lgkmcnt(6)
	v_mfma_f32_32x32x16_bf16 v[66:81], v[134:137], v[174:177], v[66:81]
	ds_read_b64_tr_b16 v[174:175], v242 offset:26624
	ds_read_b64_tr_b16 v[176:177], v242 offset:26880
	s_waitcnt lgkmcnt(6)
	v_mfma_f32_32x32x16_bf16 v[50:65], v[146:149], v[162:165], v[50:65]
	ds_read_b64_tr_b16 v[162:163], v242 offset:2560
	ds_read_b64_tr_b16 v[164:165], v242 offset:2816
	s_waitcnt lgkmcnt(6)
	v_mfma_f32_32x32x16_bf16 v[50:65], v[150:153], v[166:169], v[50:65]
	ds_read_b64_tr_b16 v[166:167], v242 offset:10752
	ds_read_b64_tr_b16 v[168:169], v242 offset:11008
	s_waitcnt lgkmcnt(6)
	v_mfma_f32_32x32x16_bf16 v[50:65], v[130:133], v[170:173], v[50:65]
	ds_read_b64_tr_b16 v[170:171], v242 offset:18944
	ds_read_b64_tr_b16 v[172:173], v242 offset:19200
	s_waitcnt lgkmcnt(6)
	v_mfma_f32_32x32x16_bf16 v[50:65], v[134:137], v[174:177], v[50:65]
	ds_read_b64_tr_b16 v[174:175], v242 offset:27136
	ds_read_b64_tr_b16 v[176:177], v242 offset:27392
	s_waitcnt lgkmcnt(6)
	v_mfma_f32_32x32x16_bf16 v[34:49], v[146:149], v[162:165], v[34:49]
	ds_read_b64_tr_b16 v[162:163], v242 offset:3072
	ds_read_b64_tr_b16 v[164:165], v242 offset:3328
	s_waitcnt lgkmcnt(6)
	v_mfma_f32_32x32x16_bf16 v[34:49], v[150:153], v[166:169], v[34:49]
	ds_read_b64_tr_b16 v[166:167], v242 offset:11264
	ds_read_b64_tr_b16 v[168:169], v242 offset:11520
	s_waitcnt lgkmcnt(6)
	v_mfma_f32_32x32x16_bf16 v[34:49], v[130:133], v[170:173], v[34:49]
	ds_read_b64_tr_b16 v[170:171], v242 offset:19456
	ds_read_b64_tr_b16 v[172:173], v242 offset:19712
	s_waitcnt lgkmcnt(6)
	v_mfma_f32_32x32x16_bf16 v[34:49], v[134:137], v[174:177], v[34:49]
	ds_read_b64_tr_b16 v[174:175], v242 offset:27648
	ds_read_b64_tr_b16 v[176:177], v242 offset:27904
	s_waitcnt lgkmcnt(6)
	v_mfma_f32_32x32x16_bf16 v[18:33], v[146:149], v[162:165], v[18:33]
	ds_read_b64_tr_b16 v[162:163], v242 offset:3584
	ds_read_b64_tr_b16 v[164:165], v242 offset:3840
	s_waitcnt lgkmcnt(6)
	v_mfma_f32_32x32x16_bf16 v[18:33], v[150:153], v[166:169], v[18:33]
	ds_read_b64_tr_b16 v[166:167], v242 offset:11776
	ds_read_b64_tr_b16 v[168:169], v242 offset:12032
	s_waitcnt lgkmcnt(6)
	v_mfma_f32_32x32x16_bf16 v[18:33], v[130:133], v[170:173], v[18:33]
	ds_read_b64_tr_b16 v[170:171], v242 offset:19968
	ds_read_b64_tr_b16 v[172:173], v242 offset:20224
	s_waitcnt lgkmcnt(6)
	v_mfma_f32_32x32x16_bf16 v[18:33], v[134:137], v[174:177], v[18:33]
	ds_read_b64_tr_b16 v[174:175], v242 offset:28160
	ds_read_b64_tr_b16 v[176:177], v242 offset:28416
	s_waitcnt lgkmcnt(6)
	v_mfma_f32_32x32x16_bf16 v[2:17], v[146:149], v[162:165], v[2:17]
	s_waitcnt lgkmcnt(4)
	v_mfma_f32_32x32x16_bf16 v[2:17], v[150:153], v[166:169], v[2:17]
	s_waitcnt lgkmcnt(2)
	v_mfma_f32_32x32x16_bf16 v[2:17], v[130:133], v[170:173], v[2:17]
	s_waitcnt lgkmcnt(0)
	v_mfma_f32_32x32x16_bf16 v[2:17], v[134:137], v[174:177], v[2:17]
	s_branch .Lat_end_a
.Lat_resc_a:
	v_max_f32_e32 v236, v233, v234
	v_sub_f32_e32 v237, v233, v236
	v_exp_f32_e32 v237, v237
	v_mov_b32_e32 v233, v236
	s_and_saveexec_b64 s[4:5], s[36:37]
	ds_write_b32 v220, v237
	s_mov_b64 exec, s[4:5]
	v_mul_f32_e32 v232, v232, v237
	v_add_u32_e32 v235, s96, v219
	s_waitcnt lgkmcnt(0)
	ds_read_b128 v[238:241], v235 offset:0
	s_waitcnt lgkmcnt(0)
	v_pk_mul_f32 v[114:115], v[114:115], v[238:239]
	v_pk_mul_f32 v[116:117], v[116:117], v[240:241]
	v_pk_mul_f32 v[98:99], v[98:99], v[238:239]
	v_pk_mul_f32 v[100:101], v[100:101], v[240:241]
	v_pk_mul_f32 v[82:83], v[82:83], v[238:239]
	v_pk_mul_f32 v[84:85], v[84:85], v[240:241]
	v_pk_mul_f32 v[66:67], v[66:67], v[238:239]
	v_pk_mul_f32 v[68:69], v[68:69], v[240:241]
	v_pk_mul_f32 v[50:51], v[50:51], v[238:239]
	v_pk_mul_f32 v[52:53], v[52:53], v[240:241]
	v_pk_mul_f32 v[34:35], v[34:35], v[238:239]
	v_pk_mul_f32 v[36:37], v[36:37], v[240:241]
	v_pk_mul_f32 v[18:19], v[18:19], v[238:239]
	v_pk_mul_f32 v[20:21], v[20:21], v[240:241]
	v_pk_mul_f32 v[2:3], v[2:3], v[238:239]
	v_pk_mul_f32 v[4:5], v[4:5], v[240:241]
	ds_read_b128 v[238:241], v235 offset:32
	s_waitcnt lgkmcnt(0)
	v_pk_mul_f32 v[118:119], v[118:119], v[238:239]
	v_pk_mul_f32 v[120:121], v[120:121], v[240:241]
	v_pk_mul_f32 v[102:103], v[102:103], v[238:239]
	v_pk_mul_f32 v[104:105], v[104:105], v[240:241]
	v_pk_mul_f32 v[86:87], v[86:87], v[238:239]
	v_pk_mul_f32 v[88:89], v[88:89], v[240:241]
	v_pk_mul_f32 v[70:71], v[70:71], v[238:239]
	v_pk_mul_f32 v[72:73], v[72:73], v[240:241]
	v_pk_mul_f32 v[54:55], v[54:55], v[238:239]
	v_pk_mul_f32 v[56:57], v[56:57], v[240:241]
	v_pk_mul_f32 v[38:39], v[38:39], v[238:239]
	v_pk_mul_f32 v[40:41], v[40:41], v[240:241]
	v_pk_mul_f32 v[22:23], v[22:23], v[238:239]
	v_pk_mul_f32 v[24:25], v[24:25], v[240:241]
	v_pk_mul_f32 v[6:7], v[6:7], v[238:239]
	v_pk_mul_f32 v[8:9], v[8:9], v[240:241]
	ds_read_b128 v[238:241], v235 offset:64
	s_waitcnt lgkmcnt(0)
	v_pk_mul_f32 v[122:123], v[122:123], v[238:239]
	v_pk_mul_f32 v[124:125], v[124:125], v[240:241]
	v_pk_mul_f32 v[106:107], v[106:107], v[238:239]
	v_pk_mul_f32 v[108:109], v[108:109], v[240:241]
	v_pk_mul_f32 v[90:91], v[90:91], v[238:239]
	v_pk_mul_f32 v[92:93], v[92:93], v[240:241]
	v_pk_mul_f32 v[74:75], v[74:75], v[238:239]
	v_pk_mul_f32 v[76:77], v[76:77], v[240:241]
	v_pk_mul_f32 v[58:59], v[58:59], v[238:239]
	v_pk_mul_f32 v[60:61], v[60:61], v[240:241]
	v_pk_mul_f32 v[42:43], v[42:43], v[238:239]
	v_pk_mul_f32 v[44:45], v[44:45], v[240:241]
	v_pk_mul_f32 v[26:27], v[26:27], v[238:239]
	v_pk_mul_f32 v[28:29], v[28:29], v[240:241]
	v_pk_mul_f32 v[10:11], v[10:11], v[238:239]
	v_pk_mul_f32 v[12:13], v[12:13], v[240:241]
	ds_read_b128 v[238:241], v235 offset:96
	s_waitcnt lgkmcnt(0)
	v_pk_mul_f32 v[126:127], v[126:127], v[238:239]
	v_pk_mul_f32 v[128:129], v[128:129], v[240:241]
	v_pk_mul_f32 v[110:111], v[110:111], v[238:239]
	v_pk_mul_f32 v[112:113], v[112:113], v[240:241]
	v_pk_mul_f32 v[94:95], v[94:95], v[238:239]
	v_pk_mul_f32 v[96:97], v[96:97], v[240:241]
	v_pk_mul_f32 v[78:79], v[78:79], v[238:239]
	v_pk_mul_f32 v[80:81], v[80:81], v[240:241]
	v_pk_mul_f32 v[62:63], v[62:63], v[238:239]
	v_pk_mul_f32 v[64:65], v[64:65], v[240:241]
	v_pk_mul_f32 v[46:47], v[46:47], v[238:239]
	v_pk_mul_f32 v[48:49], v[48:49], v[240:241]
	v_pk_mul_f32 v[30:31], v[30:31], v[238:239]
	v_pk_mul_f32 v[32:33], v[32:33], v[240:241]
	v_pk_mul_f32 v[14:15], v[14:15], v[238:239]
	v_pk_mul_f32 v[16:17], v[16:17], v[240:241]
	s_branch .Lat_exp_a
.Lat_diag_a:
	v_subrev_u32_e32 v234, 0, v223
	v_cmp_gt_i32_e64 s[4:5], 0, v234
	v_med3_i32 v234, v234, 0, s81
	v_lshl_add_u32 v234, v234, 2, s50
	ds_read_b32 v238, v234
	v_subrev_u32_e32 v235, 1, v223
	v_cmp_gt_i32_e64 s[6:7], 0, v235
	v_med3_i32 v235, v235, 0, s81
	v_lshl_add_u32 v235, v235, 2, s50
	ds_read_b32 v239, v235
	v_subrev_u32_e32 v236, 2, v223
	v_cmp_gt_i32_e64 s[8:9], 0, v236
	v_med3_i32 v236, v236, 0, s81
	v_lshl_add_u32 v236, v236, 2, s50
	ds_read_b32 v240, v236
	v_subrev_u32_e32 v237, 3, v223
	v_cmp_gt_i32_e64 s[10:11], 0, v237
	v_med3_i32 v237, v237, 0, s81
	v_lshl_add_u32 v237, v237, 2, s50
	ds_read_b32 v241, v237
	s_waitcnt lgkmcnt(0)
	v_add_f32_e32 v146, v146, v238
	v_cndmask_b32_e64 v146, v146, v216, s[4:5]
	v_add_f32_e32 v147, v147, v239
	v_cndmask_b32_e64 v147, v147, v216, s[6:7]
	v_add_f32_e32 v148, v148, v240
	v_cndmask_b32_e64 v148, v148, v216, s[8:9]
	v_add_f32_e32 v149, v149, v241
	v_cndmask_b32_e64 v149, v149, v216, s[10:11]
	v_subrev_u32_e32 v234, 8, v223
	v_cmp_gt_i32_e64 s[4:5], 0, v234
	v_med3_i32 v234, v234, 0, s81
	v_lshl_add_u32 v234, v234, 2, s50
	ds_read_b32 v238, v234
	v_subrev_u32_e32 v235, 9, v223
	v_cmp_gt_i32_e64 s[6:7], 0, v235
	v_med3_i32 v235, v235, 0, s81
	v_lshl_add_u32 v235, v235, 2, s50
	ds_read_b32 v239, v235
	v_subrev_u32_e32 v236, 10, v223
	v_cmp_gt_i32_e64 s[8:9], 0, v236
	v_med3_i32 v236, v236, 0, s81
	v_lshl_add_u32 v236, v236, 2, s50
	ds_read_b32 v240, v236
	v_subrev_u32_e32 v237, 11, v223
	v_cmp_gt_i32_e64 s[10:11], 0, v237
	v_med3_i32 v237, v237, 0, s81
	v_lshl_add_u32 v237, v237, 2, s50
	ds_read_b32 v241, v237
	s_waitcnt lgkmcnt(0)
	v_add_f32_e32 v150, v150, v238
	v_cndmask_b32_e64 v150, v150, v216, s[4:5]
	v_add_f32_e32 v151, v151, v239
	v_cndmask_b32_e64 v151, v151, v216, s[6:7]
	v_add_f32_e32 v152, v152, v240
	v_cndmask_b32_e64 v152, v152, v216, s[8:9]
	v_add_f32_e32 v153, v153, v241
	v_cndmask_b32_e64 v153, v153, v216, s[10:11]
	v_subrev_u32_e32 v234, 16, v223
	v_cmp_gt_i32_e64 s[4:5], 0, v234
	v_med3_i32 v234, v234, 0, s81
	v_lshl_add_u32 v234, v234, 2, s50
	ds_read_b32 v238, v234
	v_subrev_u32_e32 v235, 17, v223
	v_cmp_gt_i32_e64 s[6:7], 0, v235
	v_med3_i32 v235, v235, 0, s81
	v_lshl_add_u32 v235, v235, 2, s50
	ds_read_b32 v239, v235
	v_subrev_u32_e32 v236, 18, v223
	v_cmp_gt_i32_e64 s[8:9], 0, v236
	v_med3_i32 v236, v236, 0, s81
	v_lshl_add_u32 v236, v236, 2, s50
	ds_read_b32 v240, v236
	v_subrev_u32_e32 v237, 19, v223
	v_cmp_gt_i32_e64 s[10:11], 0, v237
	v_med3_i32 v237, v237, 0, s81
	v_lshl_add_u32 v237, v237, 2, s50
	ds_read_b32 v241, v237
	s_waitcnt lgkmcnt(0)
	v_add_f32_e32 v154, v154, v238
	v_cndmask_b32_e64 v154, v154, v216, s[4:5]
	v_add_f32_e32 v155, v155, v239
	v_cndmask_b32_e64 v155, v155, v216, s[6:7]
	v_add_f32_e32 v156, v156, v240
	v_cndmask_b32_e64 v156, v156, v216, s[8:9]
	v_add_f32_e32 v157, v157, v241
	v_cndmask_b32_e64 v157, v157, v216, s[10:11]
	v_subrev_u32_e32 v234, 24, v223
	v_cmp_gt_i32_e64 s[4:5], 0, v234
	v_med3_i32 v234, v234, 0, s81
	v_lshl_add_u32 v234, v234, 2, s50
	ds_read_b32 v238, v234
	v_subrev_u32_e32 v235, 25, v223
	v_cmp_gt_i32_e64 s[6:7], 0, v235
	v_med3_i32 v235, v235, 0, s81
	v_lshl_add_u32 v235, v235, 2, s50
	ds_read_b32 v239, v235
	v_subrev_u32_e32 v236, 26, v223
	v_cmp_gt_i32_e64 s[8:9], 0, v236
	v_med3_i32 v236, v236, 0, s81
	v_lshl_add_u32 v236, v236, 2, s50
	ds_read_b32 v240, v236
	v_subrev_u32_e32 v237, 27, v223
	v_cmp_gt_i32_e64 s[10:11], 0, v237
	v_med3_i32 v237, v237, 0, s81
	v_lshl_add_u32 v237, v237, 2, s50
	ds_read_b32 v241, v237
	s_waitcnt lgkmcnt(0)
	v_add_f32_e32 v158, v158, v238
	v_cndmask_b32_e64 v158, v158, v216, s[4:5]
	v_add_f32_e32 v159, v159, v239
	v_cndmask_b32_e64 v159, v159, v216, s[6:7]
	v_add_f32_e32 v160, v160, v240
	v_cndmask_b32_e64 v160, v160, v216, s[8:9]
	v_add_f32_e32 v161, v161, v241
	v_cndmask_b32_e64 v161, v161, v216, s[10:11]
	v_subrev_u32_e32 v234, 32, v223
	v_cmp_gt_i32_e64 s[4:5], 0, v234
	v_med3_i32 v234, v234, 0, s81
	v_lshl_add_u32 v234, v234, 2, s50
	ds_read_b32 v238, v234
	v_subrev_u32_e32 v235, 33, v223
	v_cmp_gt_i32_e64 s[6:7], 0, v235
	v_med3_i32 v235, v235, 0, s81
	v_lshl_add_u32 v235, v235, 2, s50
	ds_read_b32 v239, v235
	v_subrev_u32_e32 v236, 34, v223
	v_cmp_gt_i32_e64 s[8:9], 0, v236
	v_med3_i32 v236, v236, 0, s81
	v_lshl_add_u32 v236, v236, 2, s50
	ds_read_b32 v240, v236
	v_subrev_u32_e32 v237, 35, v223
	v_cmp_gt_i32_e64 s[10:11], 0, v237
	v_med3_i32 v237, v237, 0, s81
	v_lshl_add_u32 v237, v237, 2, s50
	ds_read_b32 v241, v237
	s_waitcnt lgkmcnt(0)
	v_add_f32_e32 v130, v130, v238
	v_cndmask_b32_e64 v130, v130, v216, s[4:5]
	v_add_f32_e32 v131, v131, v239
	v_cndmask_b32_e64 v131, v131, v216, s[6:7]
	v_add_f32_e32 v132, v132, v240
	v_cndmask_b32_e64 v132, v132, v216, s[8:9]
	v_add_f32_e32 v133, v133, v241
	v_cndmask_b32_e64 v133, v133, v216, s[10:11]
	v_subrev_u32_e32 v234, 40, v223
	v_cmp_gt_i32_e64 s[4:5], 0, v234
	v_med3_i32 v234, v234, 0, s81
	v_lshl_add_u32 v234, v234, 2, s50
	ds_read_b32 v238, v234
	v_subrev_u32_e32 v235, 41, v223
	v_cmp_gt_i32_e64 s[6:7], 0, v235
	v_med3_i32 v235, v235, 0, s81
	v_lshl_add_u32 v235, v235, 2, s50
	ds_read_b32 v239, v235
	v_subrev_u32_e32 v236, 42, v223
	v_cmp_gt_i32_e64 s[8:9], 0, v236
	v_med3_i32 v236, v236, 0, s81
	v_lshl_add_u32 v236, v236, 2, s50
	ds_read_b32 v240, v236
	v_subrev_u32_e32 v237, 43, v223
	v_cmp_gt_i32_e64 s[10:11], 0, v237
	v_med3_i32 v237, v237, 0, s81
	v_lshl_add_u32 v237, v237, 2, s50
	ds_read_b32 v241, v237
	s_waitcnt lgkmcnt(0)
	v_add_f32_e32 v134, v134, v238
	v_cndmask_b32_e64 v134, v134, v216, s[4:5]
	v_add_f32_e32 v135, v135, v239
	v_cndmask_b32_e64 v135, v135, v216, s[6:7]
	v_add_f32_e32 v136, v136, v240
	v_cndmask_b32_e64 v136, v136, v216, s[8:9]
	v_add_f32_e32 v137, v137, v241
	v_cndmask_b32_e64 v137, v137, v216, s[10:11]
	v_subrev_u32_e32 v234, 48, v223
	v_cmp_gt_i32_e64 s[4:5], 0, v234
	v_med3_i32 v234, v234, 0, s81
	v_lshl_add_u32 v234, v234, 2, s50
	ds_read_b32 v238, v234
	v_subrev_u32_e32 v235, 49, v223
	v_cmp_gt_i32_e64 s[6:7], 0, v235
	v_med3_i32 v235, v235, 0, s81
	v_lshl_add_u32 v235, v235, 2, s50
	ds_read_b32 v239, v235
	v_subrev_u32_e32 v236, 50, v223
	v_cmp_gt_i32_e64 s[8:9], 0, v236
	v_med3_i32 v236, v236, 0, s81
	v_lshl_add_u32 v236, v236, 2, s50
	ds_read_b32 v240, v236
	v_subrev_u32_e32 v237, 51, v223
	v_cmp_gt_i32_e64 s[10:11], 0, v237
	v_med3_i32 v237, v237, 0, s81
	v_lshl_add_u32 v237, v237, 2, s50
	ds_read_b32 v241, v237
	s_waitcnt lgkmcnt(0)
	v_add_f32_e32 v138, v138, v238
	v_cndmask_b32_e64 v138, v138, v216, s[4:5]
	v_add_f32_e32 v139, v139, v239
	v_cndmask_b32_e64 v139, v139, v216, s[6:7]
	v_add_f32_e32 v140, v140, v240
	v_cndmask_b32_e64 v140, v140, v216, s[8:9]
	v_add_f32_e32 v141, v141, v241
	v_cndmask_b32_e64 v141, v141, v216, s[10:11]
	v_subrev_u32_e32 v234, 56, v223
	v_cmp_gt_i32_e64 s[4:5], 0, v234
	v_med3_i32 v234, v234, 0, s81
	v_lshl_add_u32 v234, v234, 2, s50
	ds_read_b32 v238, v234
	v_subrev_u32_e32 v235, 57, v223
	v_cmp_gt_i32_e64 s[6:7], 0, v235
	v_med3_i32 v235, v235, 0, s81
	v_lshl_add_u32 v235, v235, 2, s50
	ds_read_b32 v239, v235
	v_subrev_u32_e32 v236, 58, v223
	v_cmp_gt_i32_e64 s[8:9], 0, v236
	v_med3_i32 v236, v236, 0, s81
	v_lshl_add_u32 v236, v236, 2, s50
	ds_read_b32 v240, v236
	v_subrev_u32_e32 v237, 59, v223
	v_cmp_gt_i32_e64 s[10:11], 0, v237
	v_med3_i32 v237, v237, 0, s81
	v_lshl_add_u32 v237, v237, 2, s50
	ds_read_b32 v241, v237
	s_waitcnt lgkmcnt(0)
	v_add_f32_e32 v142, v142, v238
	v_cndmask_b32_e64 v142, v142, v216, s[4:5]
	v_add_f32_e32 v143, v143, v239
	v_cndmask_b32_e64 v143, v143, v216, s[6:7]
	v_add_f32_e32 v144, v144, v240
	v_cndmask_b32_e64 v144, v144, v216, s[8:9]
	v_add_f32_e32 v145, v145, v241
	v_cndmask_b32_e64 v145, v145, v216, s[10:11]
	s_branch .Lat_sm_a
.Lat_end_a:
.Lat_next:
	s_add_i32 s58, s58, 1
	s_xor_b32 s70, s70, 0x10000
	s_xor_b32 s71, s71, 0x10000
	v_add_u32_e32 v223, 0xffffffc0, v223
	s_addk_i32 s91, 0x40
	s_cmp_le_u32 s58, s88
	s_cbranch_scc1 .Lat_loop
	s_waitcnt vmcnt(0) lgkmcnt(0)
	s_barrier
	s_cmp_gt_u32 s58, s89
	s_cbranch_scc1 .Lat_done
	v_xor_b32_e32 v234, s70, v221
	ds_read_b128 v[162:165], v234
	v_xor_b32_e32 v235, 32, v234
	ds_read_b128 v[166:169], v235
	v_xor_b32_e32 v236, 64, v234
	ds_read_b128 v[170:173], v236
	v_xor_b32_e32 v237, 0x60, v234
	ds_read_b128 v[174:177], v237
	v_xor_b32_e32 v238, 0x80, v234
	v_xor_b32_e32 v239, 0xa0, v234
	v_xor_b32_e32 v240, 0xc0, v234
	v_xor_b32_e32 v241, 0xe0, v234
	v_add_u32_e32 v242, s70, v222
	s_waitcnt lgkmcnt(3)
	v_mfma_f32_32x32x16_bf16 v[146:161], v[162:165], v[178:181], 0
	ds_read_b128 v[162:165], v238
	s_waitcnt lgkmcnt(3)
	v_mfma_f32_32x32x16_bf16 v[146:161], v[166:169], v[182:185], v[146:161]
	ds_read_b128 v[166:169], v239
	s_waitcnt lgkmcnt(3)
	v_mfma_f32_32x32x16_bf16 v[146:161], v[170:173], v[186:189], v[146:161]
	ds_read_b128 v[170:173], v240
	s_waitcnt lgkmcnt(3)
	v_mfma_f32_32x32x16_bf16 v[146:161], v[174:177], v[190:193], v[146:161]
	ds_read_b128 v[174:177], v241
	s_waitcnt lgkmcnt(3)
	v_mfma_f32_32x32x16_bf16 v[146:161], v[162:165], v[194:197], v[146:161]
	ds_read_b128 v[162:165], v234 offset:8192
	s_waitcnt lgkmcnt(3)
	v_mfma_f32_32x32x16_bf16 v[146:161], v[166:169], v[198:201], v[146:161]
	ds_read_b128 v[166:169], v235 offset:8192
	s_waitcnt lgkmcnt(3)
	v_mfma_f32_32x32x16_bf16 v[146:161], v[170:173], v[202:205], v[146:161]
	ds_read_b128 v[170:173], v236 offset:8192
	s_waitcnt lgkmcnt(3)
	v_mfma_f32_32x32x16_bf16 v[146:161], v[174:177], v[206:209], v[146:161]
	ds_read_b128 v[174:177], v237 offset:8192
	s_waitcnt lgkmcnt(3)
	v_mfma_f32_32x32x16_bf16 v[130:145], v[162:165], v[178:181], 0
	ds_read_b128 v[162:165], v238 offset:8192
	s_waitcnt lgkmcnt(3)
	v_mfma_f32_32x32x16_bf16 v[130:145], v[166:169], v[182:185], v[130:145]
	ds_read_b128 v[166:169], v239 offset:8192
	s_waitcnt lgkmcnt(3)
	v_mfma_f32_32x32x16_bf16 v[130:145], v[170:173], v[186:189], v[130:145]
	ds_read_b128 v[170:173], v240 offset:8192
	s_waitcnt lgkmcnt(3)
	v_mfma_f32_32x32x16_bf16 v[130:145], v[174:177], v[190:193], v[130:145]
	ds_read_b128 v[174:177], v241 offset:8192
	s_waitcnt lgkmcnt(3)
	v_mfma_f32_32x32x16_bf16 v[130:145], v[162:165], v[194:197], v[130:145]
	ds_read_b64_tr_b16 v[162:163], v242 offset:0
	ds_read_b64_tr_b16 v[164:165], v242 offset:256
	s_waitcnt lgkmcnt(4)
	v_mfma_f32_32x32x16_bf16 v[130:145], v[166:169], v[198:201], v[130:145]
	ds_read_b64_tr_b16 v[166:167], v242 offset:8192
	ds_read_b64_tr_b16 v[168:169], v242 offset:8448
	s_waitcnt lgkmcnt(5)
	v_mfma_f32_32x32x16_bf16 v[130:145], v[170:173], v[202:205], v[130:145]
	ds_read_b64_tr_b16 v[170:171], v242 offset:16384
	ds_read_b64_tr_b16 v[172:173], v242 offset:16640
	s_waitcnt lgkmcnt(6)
	v_mfma_f32_32x32x16_bf16 v[130:145], v[174:177], v[206:209], v[130:145]
	ds_read_b64_tr_b16 v[174:175], v242 offset:24576
	ds_read_b64_tr_b16 v[176:177], v242 offset:24832
	s_add_i32 s4, s91, 0xb0
	s_cmp_le_u32 s4, s3
	s_cbranch_scc0 .Lat_diag_b

.Lat_end_b:
.Lat_done:
	s_mov_b32 m0, s92
	s_branch .LBB0_353
.Lat_inactive:
	s_add_i32 m0, s71, 0x0
	s_nop 0
	global_load_lds_dwordx4 v231, s[62:63]
	v_add_u32_e32 v231, 0x80000, v231
	s_add_i32 m0, s71, 0x400
	s_nop 0
	global_load_lds_dwordx4 v229, s[62:63]
	v_add_u32_e32 v229, 0x80000, v229
	s_add_i32 m0, s71, 0x800
	s_nop 0
	global_load_lds_dwordx4 v227, s[62:63]
	v_add_u32_e32 v227, 0x80000, v227
	s_add_i32 m0, s71, 0xc00
	s_nop 0
	global_load_lds_dwordx4 v225, s[62:63]
	v_add_u32_e32 v225, 0x80000, v225
	s_add_i32 m0, s71, 0x1000
	s_nop 0
	global_load_lds_dwordx4 v230, s[62:63]
	v_add_u32_e32 v230, 0x80000, v230
	s_add_i32 m0, s71, 0x1400
	s_nop 0
	global_load_lds_dwordx4 v228, s[62:63]
	v_add_u32_e32 v228, 0x80000, v228
	s_add_i32 m0, s71, 0x1800
	s_nop 0
	global_load_lds_dwordx4 v226, s[62:63]
	v_add_u32_e32 v226, 0x80000, v226
	s_add_i32 m0, s71, 0x1c00
	s_nop 0
	global_load_lds_dwordx4 v224, s[62:63]
	v_add_u32_e32 v224, 0x80000, v224
	s_branch .Lat_next
